# rwkv_prep LoRA stage: 16 weight-fragment loads issued together before the stage barrier instead of 8 load/wait rounds
# speedup vs baseline: 1.0025x; 1.0012x over previous
.LBB0_663:
	s_or_b64 exec, exec, s[6:7]
	v_and_b32_e32 v1, 15, v82
	v_cndmask_b32_e64 v3, v245, v246, s[4:5]
	v_and_b32_e32 v64, 0xffffffcf, v82
	v_add3_u32 v5, v8, v7, v3
	v_cvt_pk_bf16_f32 v2, v6, v2
	v_cvt_pk_bf16_f32 v3, v4, v0
	v_and_b32_e32 v144, 48, v82
	v_mul_u32_u24_e32 v0, 0x48, v1
	v_ashrrev_i32_e32 v65, 31, v64
	v_lshl_add_u64 v[48:49], s[12:13], 0, v[144:145]
	v_lshl_add_u64 v[50:51], s[14:15], 0, v[144:145]
	v_lshlrev_b32_e32 v0, 1, v0
	v_lshlrev_b64 v[20:21], 7, v[64:65]
	v_add3_u32 v73, 0, v144, v0
	v_lshl_add_u64 v[52:53], v[48:49], 0, v[20:21]
	v_lshl_add_u64 v[54:55], v[50:51], 0, v[20:21]
	s_mov_b64 s[34:35], 0x1000
	v_lshl_add_u64 v[130:131], v[52:53], 0, s[34:35]
	v_lshl_add_u64 v[132:133], v[54:55], 0, s[34:35]
	global_load_dwordx4 v[162:165], v[52:53], off
	global_load_dwordx4 v[166:169], v[54:55], off
	global_load_dwordx4 v[170:173], v[52:53], off offset:2048
	global_load_dwordx4 v[174:177], v[54:55], off offset:2048
	global_load_dwordx4 v[178:181], v[130:131], off
	global_load_dwordx4 v[182:185], v[132:133], off
	global_load_dwordx4 v[186:189], v[130:131], off offset:2048
	global_load_dwordx4 v[190:193], v[132:133], off offset:2048
	global_load_dwordx4 v[194:197], v[52:53], off offset:64
	global_load_dwordx4 v[198:201], v[54:55], off offset:64
	global_load_dwordx4 v[202:205], v[52:53], off offset:2112
	global_load_dwordx4 v[206:209], v[54:55], off offset:2112
	global_load_dwordx4 v[210:213], v[130:131], off offset:64
	global_load_dwordx4 v[214:217], v[132:133], off offset:64
	global_load_dwordx4 v[218:221], v[130:131], off offset:2112
	global_load_dwordx4 v[222:225], v[132:133], off offset:2112
	ds_write_b64 v5, v[2:3]
	s_waitcnt lgkmcnt(0)
	s_barrier
	ds_read_b128 v[0:3], v73
	ds_read_b128 v[4:7], v73 offset:4608
	ds_read_b128 v[8:11], v73 offset:2304
	ds_read_b128 v[12:15], v73 offset:6912
	v_or_b32_e32 v68, 16, v64
	v_ashrrev_i32_e32 v69, 31, v68
	v_lshlrev_b64 v[36:37], 7, v[68:69]
	v_lshl_add_u64 v[74:75], v[48:49], 0, v[36:37]
	v_lshl_add_u64 v[128:129], v[50:51], 0, v[36:37]
	v_or_b32_e32 v66, 32, v64
	v_ashrrev_i32_e32 v67, 31, v66
	v_or_b32_e32 v70, 48, v82
	v_ashrrev_i32_e32 v71, 31, v70
	v_bfe_u32 v72, v82, 4, 2
	v_mul_u32_u24_e32 v65, 0x810, v72
	v_and_b32_e32 v77, 63, v82
	v_ashrrev_i32_e32 v83, 6, v82
	v_add_u32_e32 v76, s36, v83
	v_lshlrev_b32_e32 v144, 4, v77
	s_waitcnt vmcnt(0) lgkmcnt(2)
	v_mfma_f32_16x16x32_bf16 v[28:31], v[4:7], v[166:169], 0
	s_waitcnt lgkmcnt(0)
	v_mfma_f32_16x16x32_bf16 v[32:35], v[12:15], v[166:169], 0
	v_mfma_f32_16x16x32_bf16 v[24:27], v[0:3], v[162:165], 0
	v_mfma_f32_16x16x32_bf16 v[16:19], v[8:11], v[162:165], 0
	v_mfma_f32_16x16x32_bf16 v[44:47], v[4:7], v[174:177], 0
	v_mfma_f32_16x16x32_bf16 v[60:63], v[12:15], v[174:177], 0
	v_lshlrev_b64 v[36:37], 7, v[66:67]
	v_lshl_add_u64 v[130:131], v[48:49], 0, v[36:37]
	v_lshl_add_u64 v[132:133], v[50:51], 0, v[36:37]
	v_mfma_f32_16x16x32_bf16 v[40:43], v[0:3], v[170:173], 0
	v_add_lshl_u32 v67, v65, v64, 2
	v_add_u32_e32 v69, 0, v67
	v_mfma_f32_16x16x32_bf16 v[56:59], v[8:11], v[170:173], 0
	v_mfma_f32_16x16x32_bf16 v[84:87], v[4:7], v[182:185], 0
	v_mfma_f32_16x16x32_bf16 v[92:95], v[12:15], v[182:185], 0
	v_lshlrev_b64 v[36:37], 7, v[70:71]
	v_lshl_add_u64 v[134:135], v[48:49], 0, v[36:37]
	v_lshl_add_u64 v[136:137], v[50:51], 0, v[36:37]
	v_mfma_f32_16x16x32_bf16 v[78:81], v[0:3], v[178:181], 0
	v_mfma_f32_16x16x32_bf16 v[88:91], v[8:11], v[178:181], 0
	ds_read_b128 v[112:115], v73 offset:64
	ds_read_b128 v[116:119], v73 offset:4672
	ds_read_b128 v[120:123], v73 offset:2368
	ds_read_b128 v[124:127], v73 offset:6976
	v_mfma_f32_16x16x32_bf16 v[96:99], v[0:3], v[186:189], 0
	v_mfma_f32_16x16x32_bf16 v[100:103], v[4:7], v[190:193], 0
	v_mfma_f32_16x16x32_bf16 v[104:107], v[8:11], v[186:189], 0
	v_mfma_f32_16x16x32_bf16 v[108:111], v[12:15], v[190:193], 0
	s_waitcnt lgkmcnt(3)
	v_mfma_f32_16x16x32_bf16 v[52:55], v[112:115], v[194:197], v[24:27]
	s_waitcnt lgkmcnt(2)
	v_mfma_f32_16x16x32_bf16 v[48:51], v[116:119], v[198:201], v[28:31]
	s_waitcnt lgkmcnt(1)
	v_mfma_f32_16x16x32_bf16 v[20:23], v[120:123], v[194:197], v[16:19]
	s_waitcnt lgkmcnt(0)
	v_mfma_f32_16x16x32_bf16 v[16:19], v[124:127], v[198:201], v[32:35]
	v_mfma_f32_16x16x32_bf16 v[36:39], v[112:115], v[202:205], v[40:43]
	v_mfma_f32_16x16x32_bf16 v[12:15], v[120:123], v[202:205], v[56:59]
	v_mfma_f32_16x16x32_bf16 v[32:35], v[116:119], v[206:209], v[44:47]
	v_mfma_f32_16x16x32_bf16 v[8:11], v[124:127], v[206:209], v[60:63]
	v_mfma_f32_16x16x32_bf16 v[28:31], v[112:115], v[210:213], v[78:81]
	v_mfma_f32_16x16x32_bf16 v[24:27], v[116:119], v[214:217], v[84:87]
	v_mfma_f32_16x16x32_bf16 v[4:7], v[120:123], v[210:213], v[88:91]
	s_nop 1
	v_mov_b32_e32 v85, 0
	v_mov_b32_e32 v87, 0
	v_mov_b32_e32 v84, 0
	v_mfma_f32_16x16x32_bf16 v[0:3], v[124:127], v[214:217], v[92:95]
	ds_write_b32 v69, v52 offset:9216
	v_add_u32_e32 v52, s50, v67
	ds_write_b32 v52, v48
	v_mad_u32_u24 v48, v72, s67, v247
	v_add_u32_e32 v52, v48, v64
	v_lshl_add_u32 v52, v52, 2, s50
	ds_write_b32 v69, v53 offset:11280
	ds_write_b32 v52, v49
	v_mad_u32_u24 v49, v72, s67, v248
	v_add_u32_e32 v52, v49, v64
	v_lshl_add_u32 v52, v52, 2, s50
	ds_write_b32 v69, v54 offset:13344
	ds_write_b32 v52, v50
	v_mad_u32_u24 v50, v72, s67, v249
	v_add_u32_e32 v52, v50, v64
	v_lshl_add_u32 v52, v52, 2, s50
	ds_write_b32 v69, v55 offset:15408
	ds_write_b32 v52, v51
	ds_write_b32 v69, v36 offset:9280
	v_add_lshl_u32 v36, v65, v68, 2
	v_add_u32_e32 v51, s50, v36
	ds_write_b32 v51, v32
	v_add_u32_e32 v32, v48, v68
	v_add_u32_e32 v36, 0, v36
	v_lshl_add_u32 v32, v32, 2, s50
	ds_write_b32 v36, v37 offset:11280
	ds_write_b32 v32, v33
	v_add_u32_e32 v32, v49, v68
	v_lshl_add_u32 v32, v32, 2, s50
	ds_write_b32 v36, v38 offset:13344
	ds_write_b32 v32, v34
	v_add_u32_e32 v32, v50, v68
	v_lshl_add_u32 v32, v32, 2, s50
	ds_write_b32 v36, v39 offset:15408
	ds_write_b32 v32, v35
	ds_write_b32 v69, v28 offset:9344
	v_add_lshl_u32 v28, v65, v66, 2
	v_add_u32_e32 v32, s50, v28
	ds_write_b32 v32, v24
	v_add_u32_e32 v24, v48, v66
	v_add_u32_e32 v28, 0, v28
	v_lshl_add_u32 v24, v24, 2, s50
	ds_write_b32 v28, v29 offset:11280
	ds_write_b32 v24, v25
	v_add_u32_e32 v24, v49, v66
	v_lshl_add_u32 v24, v24, 2, s50
	v_mfma_f32_16x16x32_bf16 v[56:59], v[116:119], v[222:225], v[100:103]
	ds_write_b32 v28, v30 offset:13344
	ds_write_b32 v24, v26
	v_add_u32_e32 v24, v50, v66
	v_lshl_add_u32 v24, v24, 2, s50
	v_mfma_f32_16x16x32_bf16 v[60:63], v[112:115], v[218:221], v[96:99]
	ds_write_b32 v28, v31 offset:15408
	ds_write_b32 v24, v27
	v_add_lshl_u32 v24, v65, v70, 2
	v_add_u32_e32 v25, 0, v24
	v_add_u32_e32 v24, s50, v24
	ds_write_b32 v24, v56
	v_add_u32_e32 v24, v48, v70
	v_lshl_add_u32 v24, v24, 2, s50
	ds_write_b32 v25, v60 offset:9216
	ds_write_b32 v25, v61 offset:11280
	ds_write_b32 v24, v57
	v_add_u32_e32 v24, v49, v70
	v_lshl_add_u32 v24, v24, 2, s50
	ds_write_b32 v25, v62 offset:13344
	ds_write_b32 v24, v58
	v_add_u32_e32 v24, v50, v70
	v_lshl_add_u32 v24, v24, 2, s50
	ds_write_b32 v25, v63 offset:15408
	ds_write_b32 v24, v59
	v_mad_u32_u24 v24, v72, s67, v250
	v_add_u32_e32 v26, v24, v64
	ds_write_b32 v69, v20 offset:42240
	v_lshl_add_u32 v20, v26, 2, s50
	ds_write_b32 v20, v16
	v_mad_u32_u24 v16, v72, s67, v251
	v_add_u32_e32 v20, v16, v64
	v_lshl_add_u32 v20, v20, 2, s50
	ds_write_b32 v69, v21 offset:44304
	ds_write_b32 v20, v17
	v_mad_u32_u24 v17, v72, s67, v252
	v_add_u32_e32 v20, v17, v64
	v_lshl_add_u32 v20, v20, 2, s50
	ds_write_b32 v69, v22 offset:46368
	ds_write_b32 v20, v18
	v_mad_u32_u24 v18, v72, s67, v253
	v_add_u32_e32 v20, v18, v64
	v_lshl_add_u32 v20, v20, 2, s50
	ds_write_b32 v69, v23 offset:48432
	ds_write_b32 v20, v19
	v_add_u32_e32 v19, v24, v68
	ds_write_b32 v36, v12 offset:42240
	v_lshl_add_u32 v12, v19, 2, s50
	ds_write_b32 v12, v8
	v_add_u32_e32 v8, v16, v68
	v_lshl_add_u32 v8, v8, 2, s50
	ds_write_b32 v36, v13 offset:44304
	ds_write_b32 v8, v9
	v_add_u32_e32 v8, v17, v68
	v_lshl_add_u32 v8, v8, 2, s50
	ds_write_b32 v36, v14 offset:46368
	ds_write_b32 v8, v10
	v_add_u32_e32 v8, v18, v68
	v_lshl_add_u32 v8, v8, 2, s50
	ds_write_b32 v36, v15 offset:48432
	ds_write_b32 v8, v11
	v_add_u32_e32 v8, v24, v66
	ds_write_b32 v28, v4 offset:42240
	v_lshl_add_u32 v4, v8, 2, s50
	ds_write_b32 v4, v0
	v_add_u32_e32 v0, v16, v66
	v_lshl_add_u32 v0, v0, 2, s50
	ds_write_b32 v28, v5 offset:44304
	ds_write_b32 v0, v1
	v_add_u32_e32 v0, v17, v66
	v_lshl_add_u32 v0, v0, 2, s50
	v_mfma_f32_16x16x32_bf16 v[44:47], v[120:123], v[218:221], v[104:107]
	ds_write_b32 v28, v6 offset:46368
	ds_write_b32 v0, v2
	v_add_u32_e32 v0, v18, v66
	v_mfma_f32_16x16x32_bf16 v[40:43], v[124:127], v[222:225], v[108:111]
	v_lshl_add_u32 v0, v0, 2, s50
	ds_write_b32 v28, v7 offset:48432
	ds_write_b32 v0, v3
	v_add_u32_e32 v0, v24, v70
	v_lshl_add_u32 v0, v0, 2, s50
	ds_write_b32 v25, v44 offset:42240
	s_nop 1
	ds_write_b32 v0, v40
	v_add_u32_e32 v0, v16, v70
	v_lshl_add_u32 v0, v0, 2, s50
	ds_write_b32 v25, v45 offset:44304
	ds_write_b32 v0, v41
	v_add_u32_e32 v0, v17, v70
	v_lshl_add_u32 v0, v0, 2, s50
	ds_write_b32 v25, v46 offset:46368
	ds_write_b32 v0, v42
	v_add_u32_e32 v0, v18, v70
	v_lshl_add_u32 v0, v0, 2, s50
	v_lshlrev_b32_e32 v28, 5, v77
	ds_write_b32 v25, v47 offset:48432
	ds_write_b32 v0, v43
	s_waitcnt lgkmcnt(0)
	s_barrier
	global_load_dwordx4 v[20:23], v28, s[10:11] offset:16
	global_load_dwordx4 v[48:51], v28, s[10:11]
	global_load_dwordx4 v[56:59], v28, s[10:11] offset:2320
	global_load_dwordx4 v[60:63], v28, s[10:11] offset:2304
	global_load_dwordx4 v[12:15], v28, s[16:17] offset:16
	global_load_dwordx4 v[40:43], v28, s[16:17]
	global_load_dwordx4 v[24:27], v28, s[18:19] offset:16
	global_load_dwordx4 v[52:55], v28, s[18:19]
	global_load_dwordx4 v[16:19], v28, s[20:21] offset:16
	global_load_dwordx4 v[44:47], v28, s[20:21]
	global_load_dwordx4 v[4:7], v28, s[22:23] offset:16
	global_load_dwordx4 v[32:35], v28, s[22:23]
	global_load_dwordx4 v[8:11], v28, s[24:25] offset:16
	global_load_dwordx4 v[36:39], v28, s[24:25]
	global_load_dwordx4 v[0:3], v28, s[26:27] offset:16
	s_nop 0
	global_load_dwordx4 v[28:31], v28, s[26:27]
	v_subrev_u32_e32 v88, 24, v76
	v_mov_b64_e32 v[64:65], s[8:9]
	v_mad_i64_i32 v[64:65], s[4:5], v88, s62, v[64:65]
	v_lshl_add_u64 v[64:65], v[64:65], 0, v[144:145]
	v_lshl_add_u64 v[78:79], v[64:65], 0, s[88:89]
	v_add_co_u32_e32 v64, vcc, 0x1000, v64
	v_and_b32_e32 v98, 0xfff, v88
	s_nop 0
	v_addc_co_u32_e32 v65, vcc, 0, v65, vcc
	global_load_dwordx4 v[72:75], v[64:65], off offset:2048
	global_load_dwordx4 v[68:71], v[78:79], off offset:1152
	s_nop 0
	global_load_dwordx4 v[64:67], v[78:79], off offset:2176
	v_cmp_ne_u32_e32 vcc, 0, v98
	v_mov_b32_e32 v116, 0
	v_mov_b32_e32 v115, 0
	v_mov_b32_e32 v114, 0
	v_mov_b32_e32 v112, 0
	v_mov_b32_e32 v109, 0
	v_mov_b32_e32 v107, 0
	v_mov_b32_e32 v105, 0
	v_mov_b32_e32 v103, 0
	v_mov_b32_e32 v113, 0
	v_mov_b32_e32 v111, 0
	v_mov_b32_e32 v106, 0
	v_mov_b32_e32 v102, 0
	v_mov_b32_e32 v101, 0
	v_mov_b32_e32 v100, 0
	v_mov_b32_e32 v110, 0
	v_mov_b32_e32 v108, 0
	v_mov_b32_e32 v104, 0
	v_mov_b32_e32 v86, 0
	v_mov_b32_e32 v95, 0
	v_mov_b32_e32 v93, 0
	v_mov_b32_e32 v91, 0
	s_and_saveexec_b64 s[4:5], vcc
	s_cbranch_execz .LBB0_665
	v_add_co_u32_e32 v80, vcc, 0xffffc000, v78
	s_movk_i32 s0, 0xd000
	s_nop 0
	v_addc_co_u32_e32 v81, vcc, -1, v79, vcc
	global_load_dwordx4 v[94:97], v[80:81], off offset:-512
	s_waitcnt vmcnt(0)
	v_lshlrev_b32_e32 v84, 16, v95
	v_and_b32_e32 v104, 0xffff0000, v95
	v_lshlrev_b32_e32 v86, 16, v96
	v_and_b32_e32 v95, 0xffff0000, v96
	v_add_co_u32_e32 v96, vcc, s0, v78
	v_lshlrev_b32_e32 v93, 16, v97
	v_and_b32_e32 v91, 0xffff0000, v97
	v_addc_co_u32_e32 v97, vcc, -1, v79, vcc
	global_load_dwordx4 v[78:81], v[96:97], off offset:-3456
	v_lshlrev_b32_e32 v110, 16, v94
	v_and_b32_e32 v108, 0xffff0000, v94
	s_waitcnt vmcnt(0)
	v_lshlrev_b32_e32 v113, 16, v78
	v_and_b32_e32 v111, 0xffff0000, v78
	v_lshlrev_b32_e32 v85, 16, v79
	v_and_b32_e32 v106, 0xffff0000, v79
	v_lshlrev_b32_e32 v87, 16, v80
	v_and_b32_e32 v102, 0xffff0000, v80
	v_lshlrev_b32_e32 v101, 16, v81
	v_and_b32_e32 v100, 0xffff0000, v81
	global_load_dwordx4 v[78:81], v[96:97], off offset:-2432
	s_waitcnt vmcnt(0)
	v_lshlrev_b32_e32 v116, 16, v78
	v_and_b32_e32 v115, 0xffff0000, v78
	v_lshlrev_b32_e32 v114, 16, v79
	v_and_b32_e32 v112, 0xffff0000, v79
	v_lshlrev_b32_e32 v109, 16, v80
	v_and_b32_e32 v107, 0xffff0000, v80
	v_lshlrev_b32_e32 v105, 16, v81
	v_and_b32_e32 v103, 0xffff0000, v81
